# v47 + attention softmax: row max / row sum cross-lane reductions via v_permlane16_swap / v_permlane32_swap instead of ds_swizzle / ds_bpermute round trips
# speedup vs baseline: 1.0053x; 1.0001x over previous
; __device__ __forceinline__ void attn_phase(Frame& F, h16* Obr) {
;     ...
;         const int ql = 16 * w + q16;
;         const int clo = ql > 64 - idx0 ? ql : 64 - idx0, chi = (ql + 128) < (L + 63 - idx0) ? (ql + 128) : (L + 63 - idx0);
;         const unsigned span = (unsigned)(chi - clo); const int cb = 16 * w + 4 * g - clo;
;         float mx = -3.0e38f;
; #pragma unroll
;         for (int tt = 0; tt < 9; ++tt)
; #pragma unroll
;             for (int e = 0; e < 4; ++e) { const bool ok = (unsigned)(cb + 16 * tt + e) <= span; sc[tt][e] = ok ? sc[tt][e] : -3.0e38f; mx = fmaxf(mx, sc[tt][e]); }
;         mx = fmaxf(mx, shx<16>(mx)); mx = fmaxf(mx, shx<32>(mx));
;         float den = 0.f;
; #pragma unroll
;         for (int tt = 0; tt < 9; ++tt)
; #pragma unroll
;             for (int e = 0; e < 4; ++e) { const float pv = __builtin_amdgcn_exp2f(sc[tt][e] - mx); sc[tt][e] = pv; den += pv; }
;         den += shx<16>(den); den += shx<32>(den);
.Lattn_sm:
	s_sub_i32 s0, 64, s51
	s_mul_hi_u32 s1, s23, 0xc000
	v_readlane_b32 s4, v251, 0
	v_readlane_b32 s6, v251, 2
	v_readlane_b32 s7, v251, 3
	v_readlane_b32 s5, v251, 1
	s_nop 3
	s_nop 4
	v_max_i32_e32 v88, s0, v158
	s_sub_i32 s0, s50, s51
	s_add_i32 s0, s0, 63
	v_min_i32_e32 v89, s0, v161
	v_sub_u32_e32 v89, v89, v88
	v_sub_u32_e32 v88, v162, v88
	v_cmp_le_u32_e32 vcc, v88, v89
	v_add_u32_e32 v91, 1, v88
	v_add_u32_e32 v93, 2, v88
	v_cndmask_b32_e32 v90, v246, v100, vcc
	v_cmp_le_u32_e32 vcc, v91, v89
	v_add_u32_e32 v94, 3, v88
	v_add_u32_e32 v95, 16, v88
	v_cndmask_b32_e32 v91, v246, v101, vcc
	v_cmp_le_u32_e32 vcc, v93, v89
	v_add_u32_e32 v96, 17, v88
	v_add_u32_e32 v97, 18, v88
	v_cndmask_b32_e32 v93, v246, v102, vcc
	v_cmp_le_u32_e32 vcc, v94, v89
	v_add_u32_e32 v98, 19, v88
	v_add_u32_e32 v99, 32, v88
	v_cndmask_b32_e32 v94, v246, v103, vcc
	v_cmp_le_u32_e32 vcc, v95, v89
	v_add_u32_e32 v100, 33, v88
	v_add_u32_e32 v101, 34, v88
	v_cndmask_b32_e32 v95, v246, v104, vcc
	v_cmp_le_u32_e32 vcc, v96, v89
	v_add_u32_e32 v102, 35, v88
	v_add_u32_e32 v103, 48, v88
	v_cndmask_b32_e32 v96, v246, v105, vcc
	v_cmp_le_u32_e32 vcc, v97, v89
	v_add_u32_e32 v104, 49, v88
	v_add_u32_e32 v105, 50, v88
	v_cndmask_b32_e32 v97, v246, v106, vcc
	v_cmp_le_u32_e32 vcc, v98, v89
	v_add_u32_e32 v106, 51, v88
	s_mov_b32 s0, 0xff61b1e6
	v_cndmask_b32_e32 v98, v246, v107, vcc
	v_cmp_le_u32_e32 vcc, v99, v89
	v_add_u32_e32 v107, 64, v88
	v_max3_f32 v92, v90, s0, v91
	v_cndmask_b32_e32 v99, v246, v108, vcc
	v_cmp_le_u32_e32 vcc, v100, v89
	v_add_u32_e32 v108, 0x41, v88
	v_max3_f32 v92, v92, v93, v94
	v_cndmask_b32_e32 v100, v246, v109, vcc
	v_cmp_le_u32_e32 vcc, v101, v89
	v_add_u32_e32 v109, 0x42, v88
	v_max3_f32 v92, v92, v95, v96
	v_cndmask_b32_e32 v101, v246, v110, vcc
	v_cmp_le_u32_e32 vcc, v102, v89
	v_add_u32_e32 v110, 0x43, v88
	v_max3_f32 v92, v92, v97, v98
	v_cndmask_b32_e32 v102, v246, v111, vcc
	v_cmp_le_u32_e32 vcc, v103, v89
	v_add_u32_e32 v111, 0x50, v88
	v_max3_f32 v92, v92, v99, v100
	v_cndmask_b32_e32 v103, v246, v112, vcc
	v_cmp_le_u32_e32 vcc, v104, v89
	v_add_u32_e32 v112, 0x51, v88
	v_max3_f32 v92, v92, v101, v102
	v_cndmask_b32_e32 v104, v246, v113, vcc
	v_cmp_le_u32_e32 vcc, v105, v89
	v_add_u32_e32 v113, 0x52, v88
	v_max3_f32 v92, v92, v103, v104
	v_cndmask_b32_e32 v105, v246, v114, vcc
	v_cmp_le_u32_e32 vcc, v106, v89
	v_add_u32_e32 v114, 0x53, v88
	s_mul_i32 s0, s23, 0xc000
	v_cndmask_b32_e32 v106, v246, v115, vcc
	v_cmp_le_u32_e32 vcc, v107, v89
	v_add_u32_e32 v115, 0x60, v88
	v_max3_f32 v92, v92, v105, v106
	v_cndmask_b32_e32 v107, v246, v116, vcc
	v_cmp_le_u32_e32 vcc, v108, v89
	v_add_u32_e32 v116, 0x61, v88
	s_add_u32 s0, s0, s28
	v_cndmask_b32_e32 v108, v246, v117, vcc
	v_cmp_le_u32_e32 vcc, v109, v89
	v_add_u32_e32 v117, 0x62, v88
	v_max3_f32 v92, v92, v107, v108
	v_cndmask_b32_e32 v109, v246, v118, vcc
	v_cmp_le_u32_e32 vcc, v110, v89
	v_add_u32_e32 v118, 0x63, v88
	s_addc_u32 s1, s1, s29
	v_cndmask_b32_e32 v110, v246, v119, vcc
	v_cmp_le_u32_e32 vcc, v111, v89
	v_add_u32_e32 v119, 0x70, v88
	v_max3_f32 v92, v92, v109, v110
	v_cndmask_b32_e32 v111, v246, v120, vcc
	v_cmp_le_u32_e32 vcc, v112, v89
	v_add_u32_e32 v120, 0x71, v88
	s_lshl_b32 s2, s22, 7
	v_cndmask_b32_e32 v112, v246, v121, vcc
	v_cmp_le_u32_e32 vcc, v113, v89
	v_add_u32_e32 v121, 0x72, v88
	v_max3_f32 v92, v92, v111, v112
	v_cndmask_b32_e32 v113, v246, v122, vcc
	v_cmp_le_u32_e32 vcc, v114, v89
	v_add_u32_e32 v122, 0x73, v88
	s_nop 0
	v_cndmask_b32_e32 v114, v246, v123, vcc
	v_cmp_le_u32_e32 vcc, v115, v89
	v_max3_f32 v92, v92, v113, v114
	v_add_u32_e32 v123, 0x80, v88
	v_cndmask_b32_e32 v115, v246, v124, vcc
	v_cmp_le_u32_e32 vcc, v116, v89
	s_nop 1
	v_cndmask_b32_e32 v116, v246, v125, vcc
	v_cmp_le_u32_e32 vcc, v117, v89
	v_max3_f32 v92, v92, v115, v116
	s_nop 0
	v_cndmask_b32_e32 v117, v246, v126, vcc
	v_cmp_le_u32_e32 vcc, v118, v89
	s_nop 1
	v_cndmask_b32_e32 v118, v246, v127, vcc
	v_cmp_le_u32_e32 vcc, v119, v89
	v_max3_f32 v92, v92, v117, v118
	s_nop 0
	v_cndmask_b32_e32 v119, v246, v130, vcc
	v_cmp_le_u32_e32 vcc, v120, v89
	s_nop 1
	v_cndmask_b32_e32 v120, v246, v131, vcc
	v_cmp_le_u32_e32 vcc, v121, v89
	v_max3_f32 v92, v92, v119, v120
	s_nop 0
	v_cndmask_b32_e32 v121, v246, v132, vcc
	v_cmp_le_u32_e32 vcc, v122, v89
	s_nop 1
	v_cndmask_b32_e32 v122, v246, v133, vcc
	v_cmp_le_u32_e32 vcc, v123, v89
	v_add_u32_e32 v123, 0x81, v88
	v_max3_f32 v92, v92, v121, v122
	v_cndmask_b32_e32 v84, v246, v84, vcc
	v_cmp_le_u32_e32 vcc, v123, v89
	v_add_u32_e32 v123, 0x82, v88
	v_add_u32_e32 v88, 0x83, v88
	v_cndmask_b32_e32 v85, v246, v85, vcc
	v_cmp_le_u32_e32 vcc, v123, v89
	v_max3_f32 v92, v92, v84, v85
	s_nop 0
	v_cndmask_b32_e32 v86, v246, v86, vcc
	v_cmp_le_u32_e32 vcc, v88, v89
	s_nop 1
	v_cndmask_b32_e32 v87, v246, v87, vcc
	v_max3_f32 v88, v92, v86, v87
	v_mov_b32_e32 v89, v88
	s_nop 1
	v_permlane16_swap_b32_e32 v88, v89
	v_max_f32_e32 v88, v88, v89
	v_mov_b32_e32 v89, v88
	s_nop 1
	v_permlane32_swap_b32_e32 v88, v89
	v_max_f32_e32 v194, v88, v89
	v_sub_f32_e32 v88, v90, v194
	v_exp_f32_e32 v88, v88
	v_sub_f32_e32 v90, v91, v194
	v_exp_f32_e32 v90, v90
	v_sub_f32_e32 v91, v93, v194
	v_exp_f32_e32 v91, v91
	v_sub_f32_e32 v92, v94, v194
	v_exp_f32_e32 v92, v92
	v_sub_f32_e32 v93, v95, v194
	v_add_f32_e32 v89, 0, v88
	v_exp_f32_e32 v93, v93
	v_sub_f32_e32 v94, v96, v194
	v_add_f32_e32 v89, v90, v89
	v_exp_f32_e32 v94, v94
	v_sub_f32_e32 v95, v97, v194
	v_add_f32_e32 v89, v91, v89
	v_exp_f32_e32 v95, v95
	v_sub_f32_e32 v96, v98, v194
	v_add_f32_e32 v89, v92, v89
	v_exp_f32_e32 v96, v96
	v_sub_f32_e32 v97, v99, v194
	v_add_f32_e32 v89, v93, v89
; __device__ __forceinline__ unsigned pk_h2(float lo, float hi) { f32x2 v = {lo, hi}; h16x2 h = __builtin_convertvector(v, h16x2); return __builtin_bit_cast(unsigned, h); }
; __device__ __forceinline__ void attn_phase(Frame& F, h16* Obr) {
;     ...
; #pragma unroll
;         for (int tt = 0; tt < 9; ++tt)
; #pragma unroll
;             for (int e = 0; e < 4; ++e) { const float pv = __builtin_amdgcn_exp2f(sc[tt][e] - mx); sc[tt][e] = pv; den += pv; }
;         den += shx<16>(den); den += shx<32>(den);
;         h16x8 Pf[5];
; #pragma unroll
;         for (int ks = 0; ks < 5; ++ks) { u32x4 wv; wv.x = pk_h2(sc[2 * ks][0], sc[2 * ks][1]); wv.y = pk_h2(sc[2 * ks][2], sc[2 * ks][3]);
;             if (ks < 4) { wv.z = pk_h2(sc[2 * ks + 1][0], sc[2 * ks + 1][1]); wv.w = pk_h2(sc[2 * ks + 1][2], sc[2 * ks + 1][3]); } else { wv.z = 0u; wv.w = 0u; }
;             Pf[ks] = __builtin_bit_cast(h16x8, wv); }
;         const float rden = 1.0f / den;
;         unsigned char* op = (unsigned char*)Obr + ((size_t)cu.br * M + cu.rowb + qtok) * 1024 + cu.h * 128 + 4 * g;
;         const float rs16 = rden * 16.0f;
;         const int qq = q16 >> 2, pp = q16 & 3;
;         typedef short s16x8 __attribute__((ext_vector_type(8)));
;         s16x4 vlo[2][5], vhi[2][5];
;     ...
;         ATT_LDV(0, 0);
; #pragma unroll
;         for (int c8 = 0; c8 < 8; ++c8) {
;             if (c8 + 1 < 8) ATT_LDV((c8 + 1) & 1, c8 + 1);
;             asm volatile("" ::: "memory");
;             f32x4 o = {0.f, 0.f, 0.f, 0.f};
; #pragma unroll
;             for (int ks = 0; ks < 5; ++ks) {
;                 const s16x8 vv = __builtin_shufflevector(vlo[c8 & 1][ks], vhi[c8 & 1][ks], 0, 1, 2, 3, 4, 5, 6, 7);
;                 o = __builtin_amdgcn_mfma_f32_16x16x32_f16(__builtin_bit_cast(h16x8, vv), Pf[ks], o, 0, 0, 0); }
;             int ov = __builtin_amdgcn_cvt_pk_fp8_f32(o[0] * rs16, o[1] * rs16, 0, false); ov = __builtin_amdgcn_cvt_pk_fp8_f32(o[2] * rs16, o[3] * rs16, ov, true);
;             *(int*)(op + 16 * c8) = ov; }
	v_exp_f32_e32 v97, v97
	v_sub_f32_e32 v98, v100, v194
	v_add_f32_e32 v89, v94, v89
	v_exp_f32_e32 v98, v98
	v_sub_f32_e32 v99, v101, v194
	v_add_f32_e32 v89, v95, v89
	v_exp_f32_e32 v99, v99
	v_sub_f32_e32 v100, v102, v194
	v_add_f32_e32 v89, v96, v89
	v_exp_f32_e32 v123, v100
	v_sub_f32_e32 v100, v103, v194
	v_add_f32_e32 v89, v97, v89
	v_exp_f32_e32 v124, v100
	v_sub_f32_e32 v100, v104, v194
	v_add_f32_e32 v89, v98, v89
	v_exp_f32_e32 v104, v100
	v_sub_f32_e32 v100, v105, v194
	v_add_f32_e32 v89, v99, v89
	v_exp_f32_e32 v105, v100
	v_sub_f32_e32 v100, v106, v194
	v_add_f32_e32 v89, v123, v89
	v_exp_f32_e32 v106, v100
	v_sub_f32_e32 v100, v107, v194
	v_add_f32_e32 v89, v124, v89
	v_exp_f32_e32 v107, v100
	v_sub_f32_e32 v100, v108, v194
	v_add_f32_e32 v89, v104, v89
	v_exp_f32_e32 v108, v100
	v_sub_f32_e32 v100, v109, v194
	v_add_f32_e32 v89, v105, v89
	v_exp_f32_e32 v109, v100
	v_sub_f32_e32 v100, v110, v194
	v_add_f32_e32 v89, v106, v89
	v_exp_f32_e32 v110, v100
	v_sub_f32_e32 v100, v111, v194
	v_add_f32_e32 v89, v107, v89
	v_exp_f32_e32 v111, v100
	v_sub_f32_e32 v100, v112, v194
	v_add_f32_e32 v89, v108, v89
	v_exp_f32_e32 v112, v100
	v_sub_f32_e32 v100, v113, v194
	v_add_f32_e32 v89, v109, v89
	v_exp_f32_e32 v113, v100
	v_sub_f32_e32 v100, v114, v194
	v_add_f32_e32 v89, v110, v89
	v_exp_f32_e32 v114, v100
	v_sub_f32_e32 v100, v115, v194
	v_add_f32_e32 v89, v111, v89
	v_exp_f32_e32 v115, v100
	v_sub_f32_e32 v100, v116, v194
	v_add_f32_e32 v89, v112, v89
	v_exp_f32_e32 v116, v100
	v_sub_f32_e32 v100, v117, v194
	v_add_f32_e32 v89, v113, v89
	v_exp_f32_e32 v117, v100
	v_sub_f32_e32 v100, v118, v194
	v_add_f32_e32 v89, v114, v89
	v_exp_f32_e32 v118, v100
	v_sub_f32_e32 v100, v119, v194
	v_add_f32_e32 v89, v115, v89
	v_exp_f32_e32 v119, v100
	v_sub_f32_e32 v100, v120, v194
	v_add_f32_e32 v89, v116, v89
	v_exp_f32_e32 v120, v100
	v_sub_f32_e32 v100, v121, v194
	v_add_f32_e32 v89, v117, v89
	v_exp_f32_e32 v121, v100
	v_sub_f32_e32 v100, v122, v194
	v_add_f32_e32 v89, v118, v89
	v_exp_f32_e32 v122, v100
	v_sub_f32_e32 v84, v84, v194
	v_add_f32_e32 v89, v119, v89
	v_exp_f32_e32 v84, v84
	v_sub_f32_e32 v85, v85, v194
	v_add_f32_e32 v89, v120, v89
	v_exp_f32_e32 v85, v85
	v_sub_f32_e32 v86, v86, v194
	v_add_f32_e32 v89, v121, v89
	v_exp_f32_e32 v86, v86
	v_sub_f32_e32 v87, v87, v194
	v_add_f32_e32 v89, v122, v89
	v_exp_f32_e32 v87, v87
	v_add_f32_e32 v89, v84, v89
	v_add_f32_e32 v89, v85, v89
	v_add_f32_e32 v89, v86, v89
	v_add_f32_e32 v89, v87, v89
	v_mov_b32_e32 v100, v89
	v_cvt_pk_f16_f32 v103, v95, v96
	v_cvt_pk_f16_f32 v96, v97, v98
	v_cvt_pk_f16_f32 v98, v124, v104
	v_add_u32_e32 v104, s49, v128
	v_permlane16_swap_b32_e32 v89, v100
	v_add_f32_e32 v125, v89, v100
	v_mov_b32_e32 v126, v125
	v_cvt_pk_f16_f32 v97, v99, v123
	v_cvt_pk_f16_f32 v99, v105, v106
	v_ashrrev_i32_e32 v105, 31, v104
	v_permlane32_swap_b32_e32 v125, v126
	v_add_f32_e32 v195, v125, v126
	v_cvt_pk_f16_f32 v100, v88, v90
	v_cvt_pk_f16_f32 v101, v91, v92
	v_cvt_pk_f16_f32 v102, v93, v94
	v_cvt_pk_f16_f32 v94, v111, v112
	v_cvt_pk_f16_f32 v95, v113, v114
	v_cvt_pk_f16_f32 v88, v115, v116
	v_cvt_pk_f16_f32 v89, v117, v118
	v_cvt_pk_f16_f32 v90, v119, v120
	v_lshl_add_u64 v[152:153], s[0:1], 0, v[104:105]
	ds_read_b64_tr_b16 v[112:113], v178
	ds_read_b64_tr_b16 v[114:115], v179 offset:4096
	ds_read_b64_tr_b16 v[116:117], v178 offset:8192
	ds_read_b64_tr_b16 v[118:119], v179 offset:12288
	ds_read_b64_tr_b16 v[124:125], v178 offset:16384
	ds_read_b64_tr_b16 v[126:127], v179 offset:20480
	ds_read_b64_tr_b16 v[132:133], v178 offset:24576
	ds_read_b64_tr_b16 v[134:135], v179 offset:28672
	ds_read_b64_tr_b16 v[136:137], v178 offset:32768
	ds_read_b64_tr_b16 v[138:139], v179 offset:36864
	v_lshlrev_b64 v[104:105], 10, v[152:153]
	s_waitcnt lgkmcnt(8)
	v_mfma_f32_16x16x32_f16 v[112:115], v[112:115], v[100:103], 0
	v_lshl_add_u64 v[104:105], s[6:7], 0, v[104:105]
	v_lshl_add_u64 v[104:105], v[104:105], 0, s[2:3]
	v_lshl_add_u64 v[154:155], v[104:105], 0, v[150:151]
	v_div_scale_f32 v104, s[0:1], v195, v195, 1.0
	v_rcp_f32_e32 v105, v104
	s_waitcnt lgkmcnt(6)
	v_mfma_f32_16x16x32_f16 v[112:115], v[116:119], v[96:99], v[112:115]
	v_cvt_pk_f16_f32 v92, v107, v108
	v_cvt_pk_f16_f32 v93, v109, v110
	v_fma_f32 v106, -v104, v105, 1.0
	v_fmac_f32_e32 v105, v106, v105
	s_waitcnt lgkmcnt(4)
	v_mfma_f32_16x16x32_f16 v[112:115], v[124:127], v[92:95], v[112:115]
	v_div_scale_f32 v106, vcc, 1.0, v195, 1.0
	v_mul_f32_e32 v107, v106, v105
	v_cvt_pk_f16_f32 v91, v121, v122
	v_fma_f32 v108, -v104, v107, v106
	v_fmac_f32_e32 v107, v108, v105
	s_waitcnt lgkmcnt(2)
	v_mfma_f32_16x16x32_f16 v[112:115], v[132:135], v[88:91], v[112:115]
	v_fma_f32 v104, -v104, v107, v106
	v_div_fmas_f32 v104, v104, v105, v107
	v_cvt_pk_f16_f32 v84, v84, v85
	v_cvt_pk_f16_f32 v85, v86, v87
	v_mov_b32_e32 v86, v209
	v_mov_b32_e32 v87, v209
	v_div_fixup_f32 v104, v104, v195, 1.0
	v_mul_f32_e32 v196, 0x41800000, v104
	ds_read_b64_tr_b16 v[140:141], v180
	ds_read_b64_tr_b16 v[142:143], v181 offset:4096
	ds_read_b64_tr_b16 v[128:129], v180 offset:8192
	ds_read_b64_tr_b16 v[130:131], v181 offset:12288
	ds_read_b64_tr_b16 v[120:121], v180 offset:16384
	ds_read_b64_tr_b16 v[122:123], v181 offset:20480
	ds_read_b64_tr_b16 v[108:109], v180 offset:24576
	ds_read_b64_tr_b16 v[110:111], v181 offset:28672
	ds_read_b64_tr_b16 v[104:105], v180 offset:32768
	ds_read_b64_tr_b16 v[106:107], v181 offset:36864
	s_waitcnt lgkmcnt(10)
	v_mfma_f32_16x16x32_f16 v[112:115], v[136:139], v[84:87], v[112:115]
	v_mov_b32_e32 v116, v209
	s_waitcnt lgkmcnt(8)
	v_mfma_f32_16x16x32_f16 v[136:139], v[140:143], v[100:103], 0
	s_waitcnt lgkmcnt(6)
; __device__ __forceinline__ void attn_phase(Frame& F, h16* Obr) {
;     ...
; #pragma unroll
;         for (int c8 = 0; c8 < 8; ++c8) {
;             if (c8 + 1 < 8) ATT_LDV((c8 + 1) & 1, c8 + 1);
;             asm volatile("" ::: "memory");
;             f32x4 o = {0.f, 0.f, 0.f, 0.f};
; #pragma unroll
;             for (int ks = 0; ks < 5; ++ks) {
;                 const s16x8 vv = __builtin_shufflevector(vlo[c8 & 1][ks], vhi[c8 & 1][ks], 0, 1, 2, 3, 4, 5, 6, 7);
;                 o = __builtin_amdgcn_mfma_f32_16x16x32_f16(__builtin_bit_cast(h16x8, vv), Pf[ks], o, 0, 0, 0); }
;             int ov = __builtin_amdgcn_cvt_pk_fp8_f32(o[0] * rs16, o[1] * rs16, 0, false); ov = __builtin_amdgcn_cvt_pk_fp8_f32(o[2] * rs16, o[3] * rs16, ov, true);
;             *(int*)(op + 16 * c8) = ov; }
	v_mfma_f32_16x16x32_f16 v[128:131], v[128:131], v[96:99], v[136:139]
	s_nop 2
	v_mul_f32_e32 v112, v112, v196
	v_mul_f32_e32 v113, v113, v196
	v_cvt_pk_fp8_f32 v116, v112, v113
	s_waitcnt lgkmcnt(4)
	v_mfma_f32_16x16x32_f16 v[120:123], v[120:123], v[92:95], v[128:131]
	v_mul_f32_e32 v112, v114, v196
	v_mul_f32_e32 v113, v115, v196
	v_cvt_pk_fp8_f32 v116, v112, v113 op_sel:[0,0,1]
	s_waitcnt lgkmcnt(2)
	v_mfma_f32_16x16x32_f16 v[108:111], v[108:111], v[88:91], v[120:123]
	global_store_dword v[154:155], v116, off
	s_waitcnt lgkmcnt(0)
	v_mfma_f32_16x16x32_f16 v[104:107], v[104:107], v[84:87], v[108:111]
	ds_read_b64_tr_b16 v[132:133], v182
	ds_read_b64_tr_b16 v[134:135], v183 offset:4096
	ds_read_b64_tr_b16 v[144:145], v182 offset:8192
	ds_read_b64_tr_b16 v[146:147], v183 offset:12288
	ds_read_b64_tr_b16 v[124:125], v182 offset:16384
	ds_read_b64_tr_b16 v[126:127], v183 offset:20480
	ds_read_b64_tr_b16 v[116:117], v182 offset:24576
	ds_read_b64_tr_b16 v[118:119], v183 offset:28672
	ds_read_b64_tr_b16 v[112:113], v182 offset:32768
	ds_read_b64_tr_b16 v[114:115], v183 offset:36864
	v_mov_b32_e32 v108, v209
	v_mul_f32_e32 v104, v196, v104
	v_mul_f32_e32 v105, v196, v105
	v_cvt_pk_fp8_f32 v108, v104, v105
	v_mul_f32_e32 v104, v196, v106
	v_mul_f32_e32 v105, v196, v107
	v_cvt_pk_fp8_f32 v108, v104, v105 op_sel:[0,0,1]
	s_waitcnt lgkmcnt(8)
	v_mfma_f32_16x16x32_f16 v[104:107], v[132:135], v[100:103], 0
	global_store_dword v[154:155], v108, off offset:16
	s_waitcnt lgkmcnt(6)
	v_mfma_f32_16x16x32_f16 v[104:107], v[144:147], v[96:99], v[104:107]
	ds_read_b64_tr_b16 v[140:141], v184
	ds_read_b64_tr_b16 v[142:143], v185 offset:4096
	ds_read_b64_tr_b16 v[136:137], v184 offset:8192
	ds_read_b64_tr_b16 v[138:139], v185 offset:12288
	ds_read_b64_tr_b16 v[128:129], v184 offset:16384
	ds_read_b64_tr_b16 v[130:131], v185 offset:20480
	ds_read_b64_tr_b16 v[120:121], v184 offset:24576
	ds_read_b64_tr_b16 v[122:123], v185 offset:28672
	ds_read_b64_tr_b16 v[108:109], v184 offset:32768
	ds_read_b64_tr_b16 v[110:111], v185 offset:36864
	s_waitcnt lgkmcnt(14)
	v_mfma_f32_16x16x32_f16 v[104:107], v[124:127], v[92:95], v[104:107]
	s_waitcnt lgkmcnt(12)
	v_mfma_f32_16x16x32_f16 v[104:107], v[116:119], v[88:91], v[104:107]
	s_waitcnt lgkmcnt(10)
	v_mfma_f32_16x16x32_f16 v[104:107], v[112:115], v[84:87], v[104:107]
	v_mov_b32_e32 v112, v209
	s_nop 6
	v_mul_f32_e32 v104, v196, v104
	v_mul_f32_e32 v105, v196, v105
	v_cvt_pk_fp8_f32 v112, v104, v105
	v_mul_f32_e32 v104, v196, v106
	v_mul_f32_e32 v105, v196, v107
	v_cvt_pk_fp8_f32 v112, v104, v105 op_sel:[0,0,1]
	global_store_dword v[154:155], v112, off offset:32
	s_waitcnt lgkmcnt(8)
	v_mfma_f32_16x16x32_f16 v[112:115], v[140:143], v[100:103], 0
	ds_read_b64_tr_b16 v[144:145], v186
	ds_read_b64_tr_b16 v[146:147], v187 offset:4096
	ds_read_b64_tr_b16 v[132:133], v186 offset:8192
	ds_read_b64_tr_b16 v[134:135], v187 offset:12288
	ds_read_b64_tr_b16 v[124:125], v186 offset:16384
	ds_read_b64_tr_b16 v[126:127], v187 offset:20480
	ds_read_b64_tr_b16 v[116:117], v186 offset:24576
	ds_read_b64_tr_b16 v[118:119], v187 offset:28672
	ds_read_b64_tr_b16 v[104:105], v186 offset:32768
	ds_read_b64_tr_b16 v[106:107], v187 offset:36864
	s_waitcnt lgkmcnt(14)
	v_mfma_f32_16x16x32_f16 v[112:115], v[136:139], v[96:99], v[112:115]
	v_mfma_f32_16x16x32_f16 v[112:115], v[128:131], v[92:95], v[112:115]
	s_waitcnt lgkmcnt(12)
	v_mfma_f32_16x16x32_f16 v[112:115], v[120:123], v[88:91], v[112:115]
	s_waitcnt lgkmcnt(10)
	v_mfma_f32_16x16x32_f16 v[108:111], v[108:111], v[84:87], v[112:115]
	s_nop 5
	v_mov_b32_e32 v112, v209
	s_nop 0
	v_mul_f32_e32 v108, v196, v108
	v_mul_f32_e32 v109, v196, v109
	v_cvt_pk_fp8_f32 v112, v108, v109
	v_mul_f32_e32 v108, v196, v110
	v_mul_f32_e32 v109, v196, v111
	v_cvt_pk_fp8_f32 v112, v108, v109 op_sel:[0,0,1]
	s_waitcnt lgkmcnt(8)
	v_mfma_f32_16x16x32_f16 v[108:111], v[144:147], v[100:103], 0
	global_store_dword v[154:155], v112, off offset:48
	ds_read_b64_tr_b16 v[140:141], v188
	ds_read_b64_tr_b16 v[142:143], v189 offset:4096
	ds_read_b64_tr_b16 v[136:137], v188 offset:8192
	ds_read_b64_tr_b16 v[138:139], v189 offset:12288
	ds_read_b64_tr_b16 v[128:129], v188 offset:16384
	ds_read_b64_tr_b16 v[130:131], v189 offset:20480
	ds_read_b64_tr_b16 v[120:121], v188 offset:24576
	ds_read_b64_tr_b16 v[122:123], v189 offset:28672
	ds_read_b64_tr_b16 v[112:113], v188 offset:32768
	ds_read_b64_tr_b16 v[114:115], v189 offset:36864
	s_waitcnt lgkmcnt(14)
; __device__ __forceinline__ void attn_phase(Frame& F, h16* Obr) {
;     ...
;         ATT_LDV(0, 0);
; #pragma unroll
;         for (int c8 = 0; c8 < 8; ++c8) {
;             if (c8 + 1 < 8) ATT_LDV((c8 + 1) & 1, c8 + 1);
;             asm volatile("" ::: "memory");
;             f32x4 o = {0.f, 0.f, 0.f, 0.f};
; #pragma unroll
;             for (int ks = 0; ks < 5; ++ks) {
;                 const s16x8 vv = __builtin_shufflevector(vlo[c8 & 1][ks], vhi[c8 & 1][ks], 0, 1, 2, 3, 4, 5, 6, 7);
;                 o = __builtin_amdgcn_mfma_f32_16x16x32_f16(__builtin_bit_cast(h16x8, vv), Pf[ks], o, 0, 0, 0); }
;             int ov = __builtin_amdgcn_cvt_pk_fp8_f32(o[0] * rs16, o[1] * rs16, 0, false); ov = __builtin_amdgcn_cvt_pk_fp8_f32(o[2] * rs16, o[3] * rs16, ov, true);
;             *(int*)(op + 16 * c8) = ov; }
;     ...
;         if (g == 0) Lse[((size_t)cu.br * M + cu.rowb + qtok) * 8 + cu.h] = (mx + __log2f(den)) * 0.69314718055994531f;
	v_mfma_f32_16x16x32_f16 v[108:111], v[132:135], v[96:99], v[108:111]
	s_waitcnt lgkmcnt(8)
	v_mfma_f32_16x16x32_f16 v[140:143], v[140:143], v[100:103], 0
	v_mfma_f32_16x16x32_f16 v[108:111], v[124:127], v[92:95], v[108:111]
	s_waitcnt lgkmcnt(6)
	v_mfma_f32_16x16x32_f16 v[136:139], v[136:139], v[96:99], v[140:143]
	v_mfma_f32_16x16x32_f16 v[108:111], v[116:119], v[88:91], v[108:111]
	s_waitcnt lgkmcnt(4)
	v_mfma_f32_16x16x32_f16 v[128:131], v[128:131], v[92:95], v[136:139]
	v_mfma_f32_16x16x32_f16 v[104:107], v[104:107], v[84:87], v[108:111]
	s_waitcnt lgkmcnt(2)
	v_mfma_f32_16x16x32_f16 v[120:123], v[120:123], v[88:91], v[128:131]
	s_nop 2
	v_mov_b32_e32 v108, v209
	s_nop 1
	v_mul_f32_e32 v104, v196, v104
	v_mul_f32_e32 v105, v196, v105
	v_cvt_pk_fp8_f32 v108, v104, v105
	s_waitcnt lgkmcnt(0)
	v_mfma_f32_16x16x32_f16 v[112:115], v[112:115], v[84:87], v[120:123]
	v_mul_f32_e32 v104, v196, v106
	v_mul_f32_e32 v105, v196, v107
	v_cvt_pk_fp8_f32 v108, v104, v105 op_sel:[0,0,1]
	v_mov_b32_e32 v120, v209
	global_store_dword v[154:155], v108, off offset:64
	s_nop 2
	v_mul_f32_e32 v112, v196, v112
	v_mul_f32_e32 v113, v196, v113
	v_cvt_pk_fp8_f32 v120, v112, v113
	v_mul_f32_e32 v112, v196, v114
	v_mul_f32_e32 v113, v196, v115
	ds_read_b64_tr_b16 v[132:133], v190
	ds_read_b64_tr_b16 v[134:135], v191 offset:4096
	ds_read_b64_tr_b16 v[124:125], v190 offset:8192
	ds_read_b64_tr_b16 v[126:127], v191 offset:12288
	ds_read_b64_tr_b16 v[116:117], v190 offset:16384
	ds_read_b64_tr_b16 v[118:119], v191 offset:20480
	ds_read_b64_tr_b16 v[108:109], v190 offset:24576
	ds_read_b64_tr_b16 v[110:111], v191 offset:28672
	ds_read_b64_tr_b16 v[104:105], v190 offset:32768
	ds_read_b64_tr_b16 v[106:107], v191 offset:36864
	v_cvt_pk_fp8_f32 v120, v112, v113 op_sel:[0,0,1]
	s_waitcnt lgkmcnt(8)
	v_mfma_f32_16x16x32_f16 v[132:135], v[132:135], v[100:103], 0
	global_store_dword v[154:155], v120, off offset:80
	ds_read_b64_tr_b16 v[140:141], v192
	ds_read_b64_tr_b16 v[142:143], v193 offset:4096
	ds_read_b64_tr_b16 v[136:137], v192 offset:8192
	ds_read_b64_tr_b16 v[138:139], v193 offset:12288
	ds_read_b64_tr_b16 v[128:129], v192 offset:16384
	ds_read_b64_tr_b16 v[130:131], v193 offset:20480
	ds_read_b64_tr_b16 v[120:121], v192 offset:24576
	ds_read_b64_tr_b16 v[122:123], v193 offset:28672
	ds_read_b64_tr_b16 v[112:113], v192 offset:32768
	ds_read_b64_tr_b16 v[114:115], v193 offset:36864
	s_waitcnt lgkmcnt(14)
	v_mfma_f32_16x16x32_f16 v[124:127], v[124:127], v[96:99], v[132:135]
	s_waitcnt lgkmcnt(8)
	v_mfma_f32_16x16x32_f16 v[100:103], v[140:143], v[100:103], 0
	v_mfma_f32_16x16x32_f16 v[116:119], v[116:119], v[92:95], v[124:127]
	s_waitcnt lgkmcnt(6)
	v_mfma_f32_16x16x32_f16 v[96:99], v[136:139], v[96:99], v[100:103]
	v_mfma_f32_16x16x32_f16 v[108:111], v[108:111], v[88:91], v[116:119]
	s_waitcnt lgkmcnt(4)
	v_mfma_f32_16x16x32_f16 v[92:95], v[128:131], v[92:95], v[96:99]
	v_mfma_f32_16x16x32_f16 v[104:107], v[104:107], v[84:87], v[108:111]
	s_waitcnt lgkmcnt(2)
	v_mfma_f32_16x16x32_f16 v[88:91], v[120:123], v[88:91], v[92:95]
	s_nop 2
	v_mov_b32_e32 v108, v209
	s_nop 1
	v_mul_f32_e32 v104, v196, v104
	v_mul_f32_e32 v105, v196, v105
	s_waitcnt lgkmcnt(0)
	v_mfma_f32_16x16x32_f16 v[84:87], v[112:115], v[84:87], v[88:91]
	v_cvt_pk_fp8_f32 v108, v104, v105
	v_mul_f32_e32 v104, v196, v106
	v_mul_f32_e32 v105, v196, v107
	v_mov_b32_e32 v88, v209
	v_cvt_pk_fp8_f32 v108, v104, v105 op_sel:[0,0,1]
	s_nop 2
	v_mul_f32_e32 v84, v196, v84
	v_mul_f32_e32 v85, v196, v85
	v_cvt_pk_fp8_f32 v88, v84, v85
	v_mul_f32_e32 v84, v196, v86
	v_mul_f32_e32 v85, v196, v87
	global_store_dword v[154:155], v108, off offset:96
	v_cvt_pk_fp8_f32 v88, v84, v85 op_sel:[0,0,1]
	global_store_dword v[154:155], v88, off offset:112
	s_and_saveexec_b64 s[28:29], s[38:39]
	s_cbranch_execz .LBB0_722
	v_log_f32_e32 v84, v195
	v_readlane_b32 s0, v252, 5
	v_readlane_b32 s1, v252, 6
	s_mov_b32 s23, s3
	v_add_f32_e32 v84, v194, v84
	v_mul_f32_e32 v86, 0x3f317218, v84
	v_lshlrev_b64 v[84:85], 5, v[152:153]
	v_lshl_add_u64 v[84:85], s[0:1], 0, v[84:85]
	v_lshl_add_u64 v[84:85], s[22:23], 2, v[84:85]
	global_store_dword v[84:85], v86, off
	s_branch .LBB0_722
